# v43 plus: final RMSNorm row loop issues all four residual-row loads up front with counted vmcnt waits instead of four load-wait-store round trips per row
# speedup vs baseline: 1.0157x; 1.0157x over previous
.LBB0_578:
	v_lshl_add_u64 v[22:23], s[56:57], 0, v[16:17]
	s_add_u32 s10, s56, s6
	s_addc_u32 s11, s57, s7
	v_add_co_u32_e32 v26, vcc, s9, v22
	s_add_i32 s16, s16, s18
	s_nop 0
	v_addc_co_u32_e32 v27, vcc, 0, v23, vcc
	global_load_dwordx2 v[22:23], v165, s[10:11]
	global_load_dwordx2 v[24:25], v[26:27], off
	global_load_dwordx2 v[32:33], v[26:27], off offset:512
	global_load_dwordx2 v[34:35], v[26:27], off offset:1024
	global_load_dwordx2 v[36:37], v[26:27], off offset:1536
	s_add_u32 s6, s6, s0
	s_addc_u32 s7, s7, s1
	v_lshl_add_u64 v[16:17], v[16:17], 0, s[2:3]
	s_cmpk_gt_i32 s16, 0x7fff
	s_waitcnt vmcnt(4)
	v_ffbh_u32_e32 v21, v23
	v_min_u32_e32 v21, 32, v21
	v_lshlrev_b64 v[22:23], v21, v[22:23]
	v_min_u32_e32 v22, 1, v22
	v_or_b32_e32 v22, v23, v22
	v_cvt_f32_u32_e32 v22, v22
	v_sub_u32_e32 v21, 32, v21
	s_waitcnt vmcnt(3)
	v_lshlrev_b32_e32 v28, 16, v24
	v_and_b32_e32 v29, 0xffff0000, v24
	v_ldexp_f32 v21, v22, v21
	v_fmamk_f32 v21, v21, 0x30800000, v20
	v_mul_f32_e32 v22, 0x4b800000, v21
	v_cmp_gt_f32_e32 vcc, s8, v21
	v_lshlrev_b32_e32 v24, 16, v25
	v_and_b32_e32 v25, 0xffff0000, v25
	v_cndmask_b32_e32 v21, v21, v22, vcc
	v_rsq_f32_e32 v21, v21
	s_nop 0
	v_mul_f32_e32 v22, 0x45800000, v21
	v_cndmask_b32_e32 v30, v21, v22, vcc
	v_pk_mul_f32 v[22:23], v[30:31], v[28:29] op_sel_hi:[0,1]
	v_pk_mul_f32 v[24:25], v[30:31], v[24:25] op_sel_hi:[0,1]
	v_pk_mul_f32 v[24:25], v[2:3], v[24:25]
	v_pk_mul_f32 v[22:23], v[0:1], v[22:23]
	global_store_dwordx4 v[18:19], v[22:25], off offset:-3072 nt
	s_waitcnt vmcnt(3)
	s_nop 0
	v_mov_b64_e32 v[22:23], v[32:33]
	v_lshlrev_b32_e32 v24, 16, v22
	v_and_b32_e32 v25, 0xffff0000, v22
	v_lshlrev_b32_e32 v22, 16, v23
	v_and_b32_e32 v23, 0xffff0000, v23
	v_pk_mul_f32 v[28:29], v[30:31], v[24:25] op_sel_hi:[0,1]
	v_pk_mul_f32 v[22:23], v[30:31], v[22:23] op_sel_hi:[0,1]
	v_pk_mul_f32 v[24:25], v[6:7], v[22:23]
	v_pk_mul_f32 v[22:23], v[4:5], v[28:29]
	global_store_dwordx4 v[18:19], v[22:25], off offset:-2048 nt
	s_waitcnt vmcnt(3)
	s_nop 0
	v_mov_b64_e32 v[22:23], v[34:35]
	v_lshlrev_b32_e32 v24, 16, v22
	v_and_b32_e32 v25, 0xffff0000, v22
	v_lshlrev_b32_e32 v22, 16, v23
	v_and_b32_e32 v23, 0xffff0000, v23
	v_pk_mul_f32 v[28:29], v[30:31], v[24:25] op_sel_hi:[0,1]
	v_pk_mul_f32 v[22:23], v[30:31], v[22:23] op_sel_hi:[0,1]
	v_pk_mul_f32 v[24:25], v[10:11], v[22:23]
	v_pk_mul_f32 v[22:23], v[8:9], v[28:29]
	global_store_dwordx4 v[18:19], v[22:25], off offset:-1024 nt
	s_waitcnt vmcnt(3)
	s_nop 0
	v_mov_b64_e32 v[22:23], v[36:37]
	v_lshlrev_b32_e32 v24, 16, v22
	v_and_b32_e32 v25, 0xffff0000, v22
	v_lshlrev_b32_e32 v22, 16, v23
	v_and_b32_e32 v23, 0xffff0000, v23
	v_pk_mul_f32 v[26:27], v[30:31], v[24:25] op_sel_hi:[0,1]
	v_pk_mul_f32 v[22:23], v[30:31], v[22:23] op_sel_hi:[0,1]
	v_pk_mul_f32 v[24:25], v[14:15], v[22:23]
	v_pk_mul_f32 v[22:23], v[12:13], v[26:27]
	global_store_dwordx4 v[18:19], v[22:25], off nt
	v_lshl_add_u64 v[18:19], v[18:19], 0, s[4:5]
	s_cbranch_scc0 .LBB0_578
